# arrival inv hoist: arrival-time buffer_inv issued right after the arrival drain, before the barrier-state LDS reads
# baseline (speedup 1.0000x reference)
; __device__ __forceinline__ void xcd_barrier(const XcdBarrier& b) {
;     asm volatile("s_waitcnt vmcnt(0)" ::: "memory");
;     __syncthreads();
;     if (threadIdx.x == 0) {
;         unsigned* bar = b.bar;
;         __builtin_amdgcn_s_waitcnt(0);
;         unsigned nloc = b.st[0], nx = b.st[1];
;         if (nloc == 0u) { xcd_barrier_complete(bar, b.x, nloc, nx); b.st[0] = nloc; b.st[1] = nx; }
.LBB0_134:
	v_readlane_b32 s0, v254, 10
	s_mul_i32 s0, s0, 11
	s_add_i32 s16, s0, 2
	v_readlane_b32 s1, v254, 11
	s_cmp_lt_i32 s16, s75
	s_cselect_b64 s[0:1], -1, 0
	s_and_b64 s[0:1], s[10:11], s[0:1]
	s_andn2_b64 vcc, exec, s[0:1]
	s_cbranch_vccnz .LBB0_147
	s_mov_b64 s[0:1], -1
	s_and_b64 vcc, exec, s[78:79]
	s_mov_b64 s[10:11], s[22:23]
	s_cbranch_vccz .LBB0_190
	s_waitcnt vmcnt(0)
	s_barrier
	s_and_saveexec_b64 s[4:5], s[72:73]
	s_cbranch_execz .LBB0_189
	v_readlane_b32 s0, v253, 47
	s_waitcnt vmcnt(0) expcnt(0) lgkmcnt(0)
	buffer_inv sc1
	s_nop 0
	v_mov_b32_e32 v0, s0
	ds_read_b32 v2, v0
	v_readlane_b32 s0, v253, 48
	s_waitcnt lgkmcnt(0)
	v_cmp_ne_u32_e32 vcc, 0, v2
	v_mov_b32_e32 v0, s0
	ds_read_b32 v0, v0
	s_cbranch_vccnz .LBB0_153
	s_mov_b32 s8, 1
	s_branch .LBB0_140

; __device__ __forceinline__ void xcd_barrier(const XcdBarrier& b) {
;     asm volatile("s_waitcnt vmcnt(0)" ::: "memory");
;     __syncthreads();
;     if (threadIdx.x == 0) {
;         unsigned* bar = b.bar;
;         __builtin_amdgcn_s_waitcnt(0);
;         unsigned nloc = b.st[0], nx = b.st[1];
;         if (nloc == 0u) { xcd_barrier_complete(bar, b.x, nloc, nx); b.st[0] = nloc; b.st[1] = nx; }
.LBB0_224:
	v_readlane_b32 s0, v254, 10
	s_mul_i32 s0, s0, 11
	s_add_i32 s18, s0, 3
	s_cmp_lt_i32 s18, s75
	v_readlane_b32 s1, v254, 11
	s_cselect_b64 s[4:5], -1, 0
	s_and_b64 s[0:1], s[6:7], s[4:5]
	s_andn2_b64 vcc, exec, s[0:1]
	s_cbranch_vccnz .LBB0_292
	s_mov_b64 s[0:1], -1
	s_and_b64 vcc, exec, s[78:79]
	s_cbranch_vccz .LBB0_279
	s_waitcnt vmcnt(0)
	s_waitcnt vmcnt(0)
	s_barrier
	s_and_saveexec_b64 s[6:7], s[72:73]
	s_cbranch_execz .LBB0_278
	v_readlane_b32 s0, v253, 47
	s_waitcnt vmcnt(0) expcnt(0) lgkmcnt(0)
	buffer_inv sc1
	s_nop 0
	v_mov_b32_e32 v0, s0
	ds_read_b32 v2, v0
	v_readlane_b32 s0, v253, 48
	s_waitcnt lgkmcnt(0)
	v_cmp_ne_u32_e32 vcc, 0, v2
	v_mov_b32_e32 v0, s0
	ds_read_b32 v0, v0
	s_cbranch_vccnz .LBB0_242
	s_mov_b32 s10, 1
	s_branch .LBB0_230

; __device__ __forceinline__ void xcd_barrier(const XcdBarrier& b) {
;     asm volatile("s_waitcnt vmcnt(0)" ::: "memory");
;     __syncthreads();
;     if (threadIdx.x == 0) {
;         unsigned* bar = b.bar;
;         __builtin_amdgcn_s_waitcnt(0);
;         unsigned nloc = b.st[0], nx = b.st[1];
;         if (nloc == 0u) { xcd_barrier_complete(bar, b.x, nloc, nx); b.st[0] = nloc; b.st[1] = nx; }
.LBB0_550:
	v_readlane_b32 s0, v254, 12
	s_add_i32 s18, s0, 4
	s_cmp_lt_i32 s18, s75
	s_cselect_b64 s[4:5], -1, 0
	s_and_b64 s[0:1], s[6:7], s[4:5]
	s_andn2_b64 vcc, exec, s[0:1]
	s_cbranch_vccnz .LBB0_618
	s_mov_b64 s[0:1], -1
	s_and_b64 vcc, exec, s[78:79]
	s_cbranch_vccz .LBB0_605
	s_waitcnt vmcnt(0)
	s_waitcnt vmcnt(0) lgkmcnt(0)
	s_barrier
	s_and_saveexec_b64 s[6:7], s[72:73]
	s_cbranch_execz .LBB0_604
	v_readlane_b32 s0, v253, 47
	s_waitcnt vmcnt(0) expcnt(0) lgkmcnt(0)
	buffer_inv sc1
	s_nop 0
	v_mov_b32_e32 v0, s0
	ds_read_b32 v2, v0
	v_readlane_b32 s0, v253, 48
	s_waitcnt lgkmcnt(0)
	v_cmp_ne_u32_e32 vcc, 0, v2
	v_mov_b32_e32 v0, s0
	ds_read_b32 v0, v0
	s_cbranch_vccnz .LBB0_568
	s_mov_b32 s10, 1
	s_branch .LBB0_556

; __device__ __forceinline__ void xcd_barrier(const XcdBarrier& b) {
;     asm volatile("s_waitcnt vmcnt(0)" ::: "memory");
;     __syncthreads();
;     if (threadIdx.x == 0) {
;         unsigned* bar = b.bar;
;         __builtin_amdgcn_s_waitcnt(0);
;         unsigned nloc = b.st[0], nx = b.st[1];
;         if (nloc == 0u) { xcd_barrier_complete(bar, b.x, nloc, nx); b.st[0] = nloc; b.st[1] = nx; }
.LBB0_709:
	v_readlane_b32 s0, v254, 12
	s_add_i32 s18, s0, 5
	s_cmp_lt_i32 s18, s75
	s_cselect_b64 s[4:5], -1, 0
	s_and_b64 s[0:1], s[38:39], s[4:5]
	s_andn2_b64 vcc, exec, s[0:1]
	s_mov_b32 s30, 0x3c800000
	s_cbranch_vccnz .LBB0_777
	s_mov_b64 s[0:1], -1
	s_and_b64 vcc, exec, s[78:79]
	s_cbranch_vccz .LBB0_764
	s_waitcnt vmcnt(0)
	s_waitcnt vmcnt(0) lgkmcnt(0)
	s_barrier
	s_and_saveexec_b64 s[6:7], s[72:73]
	s_cbranch_execz .LBB0_763
	v_readlane_b32 s0, v253, 47
	s_waitcnt vmcnt(0) expcnt(0) lgkmcnt(0)
	buffer_inv sc1
	s_nop 0
	v_mov_b32_e32 v0, s0
	ds_read_b32 v2, v0
	v_readlane_b32 s0, v253, 48
	s_waitcnt lgkmcnt(0)
	v_cmp_ne_u32_e32 vcc, 0, v2
	v_mov_b32_e32 v0, s0
	ds_read_b32 v0, v0
	s_cbranch_vccnz .LBB0_727
	s_mov_b32 s10, 1
	s_branch .LBB0_715

; __device__ __forceinline__ void xcd_barrier(const XcdBarrier& b) {
;     asm volatile("s_waitcnt vmcnt(0)" ::: "memory");
;     __syncthreads();
;     if (threadIdx.x == 0) {
;         unsigned* bar = b.bar;
;         __builtin_amdgcn_s_waitcnt(0);
;         unsigned nloc = b.st[0], nx = b.st[1];
;         if (nloc == 0u) { xcd_barrier_complete(bar, b.x, nloc, nx); b.st[0] = nloc; b.st[1] = nx; }
.LBB0_1341:
	v_readlane_b32 s0, v254, 12
	s_add_i32 s18, s0, 6
	s_cmp_lt_i32 s18, s75
	s_cselect_b64 s[4:5], -1, 0
	s_and_b64 s[0:1], s[16:17], s[4:5]
	s_andn2_b64 vcc, exec, s[0:1]
	s_cbranch_vccnz .LBB0_1409
	s_mov_b64 s[0:1], -1
	s_and_b64 vcc, exec, s[78:79]
	s_cbranch_vccz .LBB0_1396
	s_waitcnt vmcnt(0)
	s_waitcnt vmcnt(0) lgkmcnt(0)
	s_barrier
	s_and_saveexec_b64 s[6:7], s[72:73]
	s_cbranch_execz .LBB0_1395
	v_readlane_b32 s0, v253, 47
	s_waitcnt vmcnt(0) expcnt(0) lgkmcnt(0)
	buffer_inv sc1
	s_nop 0
	v_mov_b32_e32 v0, s0
	ds_read_b32 v2, v0
	v_readlane_b32 s0, v253, 48
	s_waitcnt lgkmcnt(0)
	v_cmp_ne_u32_e32 vcc, 0, v2
	v_mov_b32_e32 v0, s0
	ds_read_b32 v0, v0
	s_cbranch_vccnz .LBB0_1359
	s_mov_b32 s10, 1
	s_branch .LBB0_1347

; __device__ __forceinline__ void xcd_barrier(const XcdBarrier& b) {
;     asm volatile("s_waitcnt vmcnt(0)" ::: "memory");
;     __syncthreads();
;     if (threadIdx.x == 0) {
;         unsigned* bar = b.bar;
;         __builtin_amdgcn_s_waitcnt(0);
;         unsigned nloc = b.st[0], nx = b.st[1];
;         if (nloc == 0u) { xcd_barrier_complete(bar, b.x, nloc, nx); b.st[0] = nloc; b.st[1] = nx; }
.LBB0_1454:
	v_readlane_b32 s0, v254, 12
	s_add_i32 s18, s0, 7
	s_cmp_lt_i32 s18, s75
	s_cselect_b64 s[4:5], -1, 0
	s_and_b64 s[0:1], s[6:7], s[4:5]
	s_andn2_b64 vcc, exec, s[0:1]
	s_cbranch_vccnz .LBB0_1522
	s_mov_b64 s[0:1], -1
	s_and_b64 vcc, exec, s[78:79]
	s_cbranch_vccz .LBB0_1509
	s_waitcnt vmcnt(0)
	s_waitcnt vmcnt(0) lgkmcnt(0)
	s_barrier
	s_and_saveexec_b64 s[6:7], s[72:73]
	s_cbranch_execz .LBB0_1508
	v_readlane_b32 s0, v253, 47
	s_waitcnt vmcnt(0) expcnt(0) lgkmcnt(0)
	buffer_inv sc1
	s_nop 0
	v_mov_b32_e32 v0, s0
	ds_read_b32 v2, v0
	v_readlane_b32 s0, v253, 48
	s_waitcnt lgkmcnt(0)
	v_cmp_ne_u32_e32 vcc, 0, v2
	v_mov_b32_e32 v0, s0
	ds_read_b32 v0, v0
	s_cbranch_vccnz .LBB0_1472
	s_mov_b32 s10, 1
	s_branch .LBB0_1460

; __device__ __forceinline__ void xcd_barrier(const XcdBarrier& b) {
;     asm volatile("s_waitcnt vmcnt(0)" ::: "memory");
;     __syncthreads();
;     if (threadIdx.x == 0) {
;         unsigned* bar = b.bar;
;         __builtin_amdgcn_s_waitcnt(0);
;         unsigned nloc = b.st[0], nx = b.st[1];
;         if (nloc == 0u) { xcd_barrier_complete(bar, b.x, nloc, nx); b.st[0] = nloc; b.st[1] = nx; }
.LBB0_1572:
	v_readlane_b32 s0, v254, 12
	s_add_i32 s18, s0, 8
	s_cmp_lt_i32 s18, s75
	s_waitcnt lgkmcnt(0)
	s_cselect_b64 s[6:7], -1, 0
	s_and_b64 s[0:1], s[8:9], s[6:7]
	s_andn2_b64 vcc, exec, s[0:1]
	s_cbranch_vccnz .LBB0_1640
	s_mov_b64 s[0:1], -1
	s_and_b64 vcc, exec, s[78:79]
	s_cbranch_vccz .LBB0_1627
	s_waitcnt vmcnt(0)
	s_waitcnt vmcnt(0)
	s_barrier
	s_and_saveexec_b64 s[4:5], s[72:73]
	s_cbranch_execz .LBB0_1626
	v_readlane_b32 s0, v253, 47
	s_waitcnt vmcnt(0) expcnt(0) lgkmcnt(0)
	buffer_inv sc1
	s_nop 0
	v_mov_b32_e32 v0, s0
	ds_read_b32 v2, v0
	v_readlane_b32 s0, v253, 48
	s_waitcnt lgkmcnt(0)
	v_cmp_ne_u32_e32 vcc, 0, v2
	v_mov_b32_e32 v0, s0
	ds_read_b32 v0, v0
	s_cbranch_vccnz .LBB0_1590
	s_mov_b32 s10, 1
	s_branch .LBB0_1578

; __device__ __forceinline__ void xcd_barrier(const XcdBarrier& b) {
;     asm volatile("s_waitcnt vmcnt(0)" ::: "memory");
;     __syncthreads();
;     if (threadIdx.x == 0) {
;         unsigned* bar = b.bar;
;         __builtin_amdgcn_s_waitcnt(0);
;         unsigned nloc = b.st[0], nx = b.st[1];
;         if (nloc == 0u) { xcd_barrier_complete(bar, b.x, nloc, nx); b.st[0] = nloc; b.st[1] = nx; }
.LBB0_1657:
	v_readlane_b32 s0, v254, 12
	s_add_i32 s18, s0, 9
	s_cmp_lt_i32 s18, s75
	s_cselect_b64 s[6:7], -1, 0
	s_and_b64 s[0:1], s[4:5], s[6:7]
	s_andn2_b64 vcc, exec, s[0:1]
	s_cbranch_vccnz .LBB0_1725
	s_mov_b64 s[0:1], -1
	s_and_b64 vcc, exec, s[78:79]
	s_cbranch_vccz .LBB0_1712
	s_waitcnt vmcnt(0)
	s_waitcnt vmcnt(0)
	s_barrier
	s_and_saveexec_b64 s[4:5], s[72:73]
	s_cbranch_execz .LBB0_1711
	v_readlane_b32 s0, v253, 47
	s_waitcnt vmcnt(0) expcnt(0) lgkmcnt(0)
	buffer_inv sc1
	s_nop 0
	v_mov_b32_e32 v0, s0
	ds_read_b32 v2, v0
	v_readlane_b32 s0, v253, 48
	s_waitcnt lgkmcnt(0)
	v_cmp_ne_u32_e32 vcc, 0, v2
	v_mov_b32_e32 v0, s0
	ds_read_b32 v0, v0
	s_cbranch_vccnz .LBB0_1675
	s_mov_b32 s10, 1
	s_branch .LBB0_1663

; __device__ __forceinline__ void xcd_barrier(const XcdBarrier& b) {
;     asm volatile("s_waitcnt vmcnt(0)" ::: "memory");
;     __syncthreads();
;     if (threadIdx.x == 0) {
;         unsigned* bar = b.bar;
;         __builtin_amdgcn_s_waitcnt(0);
;         unsigned nloc = b.st[0], nx = b.st[1];
;         if (nloc == 0u) { xcd_barrier_complete(bar, b.x, nloc, nx); b.st[0] = nloc; b.st[1] = nx; }
.LBB0_1758:
	v_readlane_b32 s0, v254, 12
	s_add_i32 s18, s0, 10
	s_cmp_lt_i32 s18, s75
	s_cselect_b64 s[4:5], -1, 0
	s_and_b64 s[0:1], s[8:9], s[4:5]
	s_andn2_b64 vcc, exec, s[0:1]
	s_cbranch_vccnz .LBB0_1826
	s_mov_b64 s[0:1], -1
	s_and_b64 vcc, exec, s[78:79]
	s_cbranch_vccz .LBB0_1813
	s_waitcnt vmcnt(0)
	s_waitcnt vmcnt(0)
	s_barrier
	s_and_saveexec_b64 s[6:7], s[72:73]
	s_cbranch_execz .LBB0_1812
	v_readlane_b32 s0, v253, 47
	s_waitcnt vmcnt(0) expcnt(0) lgkmcnt(0)
	buffer_inv sc1
	s_nop 0
	v_mov_b32_e32 v0, s0
	ds_read_b32 v2, v0
	v_readlane_b32 s0, v253, 48
	s_waitcnt lgkmcnt(0)
	v_cmp_ne_u32_e32 vcc, 0, v2
	v_mov_b32_e32 v0, s0
	ds_read_b32 v0, v0
	s_cbranch_vccnz .LBB0_1776
	s_mov_b32 s10, 1
	s_branch .LBB0_1764

; __device__ __forceinline__ void xcd_barrier(const XcdBarrier& b) {
;     asm volatile("s_waitcnt vmcnt(0)" ::: "memory");
;     __syncthreads();
;     if (threadIdx.x == 0) {
;         unsigned* bar = b.bar;
;         __builtin_amdgcn_s_waitcnt(0);
;         unsigned nloc = b.st[0], nx = b.st[1];
;         if (nloc == 0u) { xcd_barrier_complete(bar, b.x, nloc, nx); b.st[0] = nloc; b.st[1] = nx; }
.LBB0_1880:
	s_waitcnt lgkmcnt(0)
	v_readlane_b32 s0, v254, 12
	s_add_i32 s18, s0, 11
	s_cmp_lt_i32 s18, s75
	s_cselect_b64 s[4:5], -1, 0
	s_and_b64 s[0:1], s[6:7], s[4:5]
	s_andn2_b64 vcc, exec, s[0:1]
	s_cbranch_vccnz .LBB0_1948
	s_mov_b64 s[0:1], -1
	s_and_b64 vcc, exec, s[78:79]
	s_cbranch_vccz .LBB0_1935
	s_waitcnt vmcnt(0)
	s_waitcnt vmcnt(0)
	s_barrier
	s_and_saveexec_b64 s[6:7], s[72:73]
	s_cbranch_execz .LBB0_1934
	v_readlane_b32 s0, v253, 47
	s_waitcnt vmcnt(0) expcnt(0) lgkmcnt(0)
	buffer_inv sc1
	s_nop 0
	v_mov_b32_e32 v0, s0
	ds_read_b32 v2, v0
	v_readlane_b32 s0, v253, 48
	s_waitcnt lgkmcnt(0)
	v_cmp_ne_u32_e32 vcc, 0, v2
	v_mov_b32_e32 v0, s0
	ds_read_b32 v0, v0
	s_cbranch_vccnz .LBB0_1898
	s_mov_b32 s10, 1
	s_branch .LBB0_1886

; __device__ __forceinline__ void xcd_barrier(const XcdBarrier& b) {
;     asm volatile("s_waitcnt vmcnt(0)" ::: "memory");
;     __syncthreads();
;     if (threadIdx.x == 0) {
;         unsigned* bar = b.bar;
;         __builtin_amdgcn_s_waitcnt(0);
;         unsigned nloc = b.st[0], nx = b.st[1];
;         if (nloc == 0u) { xcd_barrier_complete(bar, b.x, nloc, nx); b.st[0] = nloc; b.st[1] = nx; }
.LBB0_1978:
	s_mov_b64 s[0:1], -1
	s_and_b64 vcc, exec, s[78:79]
	s_cbranch_vccz .LBB0_2032
	s_waitcnt vmcnt(0)
	s_waitcnt vmcnt(0)
	s_barrier
	s_and_saveexec_b64 s[4:5], s[72:73]
	s_cbranch_execz .LBB0_2031
	v_readlane_b32 s0, v253, 47
	s_waitcnt vmcnt(0) expcnt(0) lgkmcnt(0)
	buffer_inv sc1
	s_nop 0
	v_mov_b32_e32 v0, s0
	ds_read_b32 v2, v0
	v_readlane_b32 s0, v253, 48
	s_waitcnt lgkmcnt(0)
	v_cmp_ne_u32_e32 vcc, 0, v2
	v_mov_b32_e32 v0, s0
	ds_read_b32 v0, v0
	s_cbranch_vccnz .LBB0_1995
	s_mov_b32 s8, 1
	s_branch .LBB0_1983
